# gla_out causal mask via v_cmp+v_cndmask instead of tuple copies; plus earlier load batching and convert wait relocation
# speedup vs baseline: 1.0018x; 1.0018x over previous
.LBB0_1549:
	v_bfe_u32 v104, v102, 5, 1
	v_lshlrev_b32_e32 v101, 2, v104
	v_sub_u32_e32 v34, v103, v101
	s_nop 11
	s_and_b64 vcc, exec, s[4:5]
	s_cbranch_vccnz .Lgla_mask_p1
	v_cmp_le_i32_e64 s[10:11], 0, v34
	v_cmp_le_i32_e64 s[12:13], 1, v34
	v_cmp_le_i32_e64 s[14:15], 2, v34
	v_cmp_le_i32_e64 s[40:41], 3, v34
	v_cndmask_b32_e64 v2, 0, v2, s[10:11]
	v_cmp_le_i32_e64 s[10:11], 8, v34
	v_cndmask_b32_e64 v3, 0, v3, s[12:13]
	v_cmp_le_i32_e64 s[12:13], 9, v34
	v_cndmask_b32_e64 v4, 0, v4, s[14:15]
	v_cmp_le_i32_e64 s[14:15], 10, v34
	v_cndmask_b32_e64 v5, 0, v5, s[40:41]
	v_cmp_le_i32_e64 s[40:41], 11, v34
	v_cndmask_b32_e64 v6, 0, v6, s[10:11]
	v_cmp_le_i32_e64 s[10:11], 16, v34
	v_cndmask_b32_e64 v7, 0, v7, s[12:13]
	v_cmp_le_i32_e64 s[12:13], 17, v34
	v_cndmask_b32_e64 v8, 0, v8, s[14:15]
	v_cmp_le_i32_e64 s[14:15], 18, v34
	v_cndmask_b32_e64 v9, 0, v9, s[40:41]
	v_cmp_le_i32_e64 s[40:41], 19, v34
	v_cndmask_b32_e64 v10, 0, v10, s[10:11]
	v_cmp_le_i32_e64 s[10:11], 24, v34
	v_cndmask_b32_e64 v11, 0, v11, s[12:13]
	v_cmp_le_i32_e64 s[12:13], 25, v34
	v_cndmask_b32_e64 v12, 0, v12, s[14:15]
	v_cmp_le_i32_e64 s[14:15], 26, v34
	v_cndmask_b32_e64 v13, 0, v13, s[40:41]
	v_cmp_le_i32_e64 s[40:41], 27, v34
	v_cndmask_b32_e64 v14, 0, v14, s[10:11]
	v_cndmask_b32_e64 v15, 0, v15, s[12:13]
	v_cndmask_b32_e64 v16, 0, v16, s[14:15]
	v_cndmask_b32_e64 v17, 0, v17, s[40:41]
	s_branch .LBB0_1692
.Lgla_mask_p1:
	v_cmp_le_i32_e64 s[10:11], 0, v34
	v_cmp_le_i32_e64 s[12:13], 1, v34
	v_cmp_le_i32_e64 s[14:15], 2, v34
	v_cmp_le_i32_e64 s[40:41], 3, v34
	v_cndmask_b32_e64 v18, 0, v18, s[10:11]
	v_cmp_le_i32_e64 s[10:11], 8, v34
	v_cndmask_b32_e64 v19, 0, v19, s[12:13]
	v_cmp_le_i32_e64 s[12:13], 9, v34
	v_cndmask_b32_e64 v20, 0, v20, s[14:15]
	v_cmp_le_i32_e64 s[14:15], 10, v34
	v_cndmask_b32_e64 v21, 0, v21, s[40:41]
	v_cmp_le_i32_e64 s[40:41], 11, v34
	v_cndmask_b32_e64 v22, 0, v22, s[10:11]
	v_cmp_le_i32_e64 s[10:11], 16, v34
	v_cndmask_b32_e64 v23, 0, v23, s[12:13]
	v_cmp_le_i32_e64 s[12:13], 17, v34
	v_cndmask_b32_e64 v24, 0, v24, s[14:15]
	v_cmp_le_i32_e64 s[14:15], 18, v34
	v_cndmask_b32_e64 v25, 0, v25, s[40:41]
	v_cmp_le_i32_e64 s[40:41], 19, v34
	v_cndmask_b32_e64 v26, 0, v26, s[10:11]
	v_cmp_le_i32_e64 s[10:11], 24, v34
	v_cndmask_b32_e64 v27, 0, v27, s[12:13]
	v_cmp_le_i32_e64 s[12:13], 25, v34
	v_cndmask_b32_e64 v28, 0, v28, s[14:15]
	v_cmp_le_i32_e64 s[14:15], 26, v34
	v_cndmask_b32_e64 v29, 0, v29, s[40:41]
	v_cmp_le_i32_e64 s[40:41], 27, v34
	v_cndmask_b32_e64 v30, 0, v30, s[10:11]
	v_cndmask_b32_e64 v31, 0, v31, s[12:13]
	v_cndmask_b32_e64 v32, 0, v32, s[14:15]
	v_cndmask_b32_e64 v33, 0, v33, s[40:41]
